# grid barrier: non-leader workgroups poll the cross-XCD release word directly (one release hop instead of two); per-XCD generation add dropped
# baseline (speedup 1.0000x reference)
.LBB0_189:
	s_or_b64 exec, exec, s[8:9]
	v_cvt_f32_u32_e32 v4, v2
	s_waitcnt vmcnt(0)
	v_readfirstlane_b32 s6, v3
	v_sub_u32_e32 v3, 0, v2
	v_rcp_iflag_f32_e32 v4, v4
	v_add_u32_e32 v5, s6, v1
	v_mul_f32_e32 v4, 0x4f7ffffe, v4
	v_cvt_u32_f32_e32 v4, v4
	v_mul_lo_u32 v1, v3, v4
	v_mul_hi_u32 v1, v4, v1
	v_add_u32_e32 v1, v4, v1
	v_mul_hi_u32 v1, v5, v1
	v_mul_lo_u32 v3, v1, v2
	v_sub_u32_e32 v3, v5, v3
	v_add_u32_e32 v4, 1, v1
	v_cmp_ge_u32_e32 vcc, v3, v2
	s_nop 1
	v_cndmask_b32_e32 v1, v1, v4, vcc
	v_sub_u32_e32 v4, v3, v2
	v_cndmask_b32_e32 v3, v3, v4, vcc
	v_add_u32_e32 v4, 1, v1
	v_cmp_ge_u32_e32 vcc, v3, v2
	v_add_u32_e32 v3, 1, v5
	s_nop 0
	v_cndmask_b32_e32 v1, v1, v4, vcc
	v_mul_lo_u32 v4, v2, v1
	v_add_u32_e32 v2, v4, v2
	v_cmp_ne_u32_e32 vcc, v3, v2
	s_and_saveexec_b64 s[6:7], vcc
	s_xor_b64 s[6:7], exec, s[6:7]
	s_cbranch_execz .LBB0_203
	s_waitcnt lgkmcnt(0)
	v_mov_b32_e32 v0, 0
	s_add_u32 s12, s94, 0x4c3500
	s_addc_u32 s13, s95, 0
	global_load_dword v0, v0, s[12:13] sc1
	s_waitcnt vmcnt(0)
	v_cmp_eq_u32_e32 vcc, v0, v1
	s_and_saveexec_b64 s[8:9], vcc
	s_cbranch_execz .LBB0_202
	s_add_u32 s10, s94, 0x4c0200
	s_addc_u32 s11, s95, 0
	s_mov_b32 s24, 1
	s_mov_b64 s[14:15], 0
	v_mov_b32_e32 v0, 0
	s_branch .LBB0_193

.LBB0_220:
	s_or_b64 exec, exec, s[6:7]
	s_mov_b64 s[6:7], exec
	v_mbcnt_lo_u32_b32 v0, s6, 0
	v_mbcnt_hi_u32_b32 v0, s7, v0
	v_cmp_eq_u32_e32 vcc, 0, v0
	s_waitcnt vmcnt(0)
	buffer_inv sc1
	s_and_saveexec_b64 s[8:9], vcc
	s_cbranch_execz .LBB0_222
	s_bcnt1_i32_b64 s6, s[6:7]
	v_mov_b32_e32 v0, 0x2000
	v_mov_b32_e32 v1, s6
.LBB0_222:
	s_or_b64 exec, exec, s[8:9]
	s_waitcnt vmcnt(0)

.LBB0_246:
	s_or_b64 exec, exec, s[6:7]
	v_cvt_f32_u32_e32 v4, v2
	s_waitcnt vmcnt(0)
	v_readfirstlane_b32 s4, v3
	v_sub_u32_e32 v3, 0, v2
	v_rcp_iflag_f32_e32 v4, v4
	v_add_u32_e32 v5, s4, v1
	v_mul_f32_e32 v4, 0x4f7ffffe, v4
	v_cvt_u32_f32_e32 v4, v4
	v_mul_lo_u32 v1, v3, v4
	v_mul_hi_u32 v1, v4, v1
	v_add_u32_e32 v1, v4, v1
	v_mul_hi_u32 v1, v5, v1
	v_mul_lo_u32 v3, v1, v2
	v_sub_u32_e32 v3, v5, v3
	v_add_u32_e32 v4, 1, v1
	v_cmp_ge_u32_e32 vcc, v3, v2
	s_nop 1
	v_cndmask_b32_e32 v1, v1, v4, vcc
	v_sub_u32_e32 v4, v3, v2
	v_cndmask_b32_e32 v3, v3, v4, vcc
	v_add_u32_e32 v4, 1, v1
	v_cmp_ge_u32_e32 vcc, v3, v2
	v_add_u32_e32 v3, 1, v5
	s_nop 0
	v_cndmask_b32_e32 v1, v1, v4, vcc
	v_mul_lo_u32 v4, v2, v1
	v_add_u32_e32 v2, v4, v2
	v_cmp_ne_u32_e32 vcc, v3, v2
	s_and_saveexec_b64 s[4:5], vcc
	s_xor_b64 s[4:5], exec, s[4:5]
	s_cbranch_execz .LBB0_260
	s_waitcnt lgkmcnt(0)
	v_mov_b32_e32 v0, 0
	s_add_u32 s10, s94, 0x4c3500
	s_addc_u32 s11, s95, 0
	global_load_dword v0, v0, s[10:11] sc1
	s_waitcnt vmcnt(0)
	v_cmp_eq_u32_e32 vcc, v0, v1
	s_and_saveexec_b64 s[6:7], vcc
	s_cbranch_execz .LBB0_259
	s_add_u32 s8, s94, 0x4c0200
	s_addc_u32 s9, s95, 0
	s_mov_b32 s22, 1
	s_mov_b64 s[12:13], 0
	v_mov_b32_e32 v0, 0
	s_branch .LBB0_250

.LBB0_277:
	s_or_b64 exec, exec, s[4:5]
	s_mov_b64 s[4:5], exec
	v_mbcnt_lo_u32_b32 v0, s4, 0
	v_mbcnt_hi_u32_b32 v0, s5, v0
	v_cmp_eq_u32_e32 vcc, 0, v0
	s_waitcnt vmcnt(0)
	buffer_inv sc1
	s_and_saveexec_b64 s[6:7], vcc
	s_cbranch_execz .LBB0_279
	s_bcnt1_i32_b64 s4, s[4:5]
	v_mov_b32_e32 v0, 0x2000
	v_mov_b32_e32 v1, s4
.LBB0_279:
	s_or_b64 exec, exec, s[6:7]
	s_waitcnt vmcnt(0)

.LBB0_382:
	s_or_b64 exec, exec, s[4:5]
	s_mov_b64 s[4:5], exec
	v_mbcnt_lo_u32_b32 v0, s4, 0
	v_mbcnt_hi_u32_b32 v0, s5, v0
	v_cmp_eq_u32_e32 vcc, 0, v0
	s_waitcnt vmcnt(0)
	buffer_inv sc1
	s_and_saveexec_b64 s[6:7], vcc
	s_cbranch_execz .LBB0_384
	s_bcnt1_i32_b64 s4, s[4:5]
	v_mov_b32_e32 v0, 0x2000
	v_mov_b32_e32 v1, s4
.LBB0_384:
	s_or_b64 exec, exec, s[6:7]
	s_waitcnt vmcnt(0)

.LBB0_478:
	s_or_b64 exec, exec, s[4:5]
	s_mov_b64 s[4:5], exec
	v_mbcnt_lo_u32_b32 v0, s4, 0
	v_mbcnt_hi_u32_b32 v0, s5, v0
	v_cmp_eq_u32_e32 vcc, 0, v0
	s_waitcnt vmcnt(0)
	buffer_inv sc1
	s_and_saveexec_b64 s[6:7], vcc
	s_cbranch_execz .LBB0_480
	s_bcnt1_i32_b64 s4, s[4:5]
	v_mov_b32_e32 v0, 0x2000
	v_mov_b32_e32 v1, s4
.LBB0_480:
	s_or_b64 exec, exec, s[6:7]
	s_waitcnt vmcnt(0)

.LBB0_818:
	s_or_b64 exec, exec, s[4:5]
	s_mov_b64 s[4:5], exec
	v_mbcnt_lo_u32_b32 v0, s4, 0
	v_mbcnt_hi_u32_b32 v0, s5, v0
	v_cmp_eq_u32_e32 vcc, 0, v0
	s_waitcnt vmcnt(0)
	buffer_inv sc1
	s_and_saveexec_b64 s[6:7], vcc
	s_cbranch_execz .LBB0_820
	s_bcnt1_i32_b64 s4, s[4:5]
	v_mov_b32_e32 v0, 0x2000
	v_mov_b32_e32 v1, s4
.LBB0_820:
	s_or_b64 exec, exec, s[6:7]
	s_waitcnt vmcnt(0)

.LBB0_938:
	s_or_b64 exec, exec, s[4:5]
	s_mov_b64 s[4:5], exec
	v_mbcnt_lo_u32_b32 v0, s4, 0
	v_mbcnt_hi_u32_b32 v0, s5, v0
	v_cmp_eq_u32_e32 vcc, 0, v0
	s_waitcnt vmcnt(0)
	buffer_inv sc1
	s_and_saveexec_b64 s[6:7], vcc
	s_cbranch_execz .LBB0_940
	s_bcnt1_i32_b64 s4, s[4:5]
	v_mov_b32_e32 v0, 0x2000
	v_mov_b32_e32 v1, s4
.LBB0_940:
	s_or_b64 exec, exec, s[6:7]
	s_waitcnt vmcnt(0)

.LBB0_1020:
	s_or_b64 exec, exec, s[6:7]
	v_cvt_f32_u32_e32 v4, v2
	s_waitcnt vmcnt(0)
	v_readfirstlane_b32 s4, v3
	v_sub_u32_e32 v3, 0, v2
	v_rcp_iflag_f32_e32 v4, v4
	v_add_u32_e32 v5, s4, v1
	v_mul_f32_e32 v4, 0x4f7ffffe, v4
	v_cvt_u32_f32_e32 v4, v4
	v_mul_lo_u32 v1, v3, v4
	v_mul_hi_u32 v1, v4, v1
	v_add_u32_e32 v1, v4, v1
	v_mul_hi_u32 v1, v5, v1
	v_mul_lo_u32 v3, v1, v2
	v_sub_u32_e32 v3, v5, v3
	v_add_u32_e32 v4, 1, v1
	v_cmp_ge_u32_e32 vcc, v3, v2
	s_nop 1
	v_cndmask_b32_e32 v1, v1, v4, vcc
	v_sub_u32_e32 v4, v3, v2
	v_cndmask_b32_e32 v3, v3, v4, vcc
	v_add_u32_e32 v4, 1, v1
	v_cmp_ge_u32_e32 vcc, v3, v2
	v_add_u32_e32 v3, 1, v5
	s_nop 0
	v_cndmask_b32_e32 v1, v1, v4, vcc
	v_mul_lo_u32 v4, v2, v1
	v_add_u32_e32 v2, v4, v2
	v_cmp_ne_u32_e32 vcc, v3, v2
	s_and_saveexec_b64 s[4:5], vcc
	s_xor_b64 s[4:5], exec, s[4:5]
	s_cbranch_execz .LBB0_1034
	s_waitcnt lgkmcnt(0)
	v_mov_b32_e32 v0, 0
	s_add_u32 s10, s88, 0x4c3500
	s_addc_u32 s11, s89, 0
	global_load_dword v0, v0, s[10:11] sc1
	s_waitcnt vmcnt(0)
	v_cmp_eq_u32_e32 vcc, v0, v1
	s_and_saveexec_b64 s[6:7], vcc
	s_cbranch_execz .LBB0_1033
	s_add_u32 s8, s88, 0x4c0200
	s_addc_u32 s9, s89, 0
	s_mov_b32 s22, 1
	s_mov_b64 s[12:13], 0
	v_mov_b32_e32 v0, 0
	s_branch .LBB0_1024

.LBB0_1051:
	s_or_b64 exec, exec, s[4:5]
	s_mov_b64 s[4:5], exec
	v_mbcnt_lo_u32_b32 v0, s4, 0
	v_mbcnt_hi_u32_b32 v0, s5, v0
	v_cmp_eq_u32_e32 vcc, 0, v0
	s_waitcnt vmcnt(0)
	buffer_inv sc1
	s_and_saveexec_b64 s[6:7], vcc
	s_cbranch_execz .LBB0_1053
	s_bcnt1_i32_b64 s4, s[4:5]
	v_mov_b32_e32 v0, 0x2000
	v_mov_b32_e32 v1, s4
.LBB0_1053:
	s_or_b64 exec, exec, s[6:7]
	s_waitcnt vmcnt(0)

.LBB0_1151:
	s_or_b64 exec, exec, s[4:5]
	s_mov_b64 s[4:5], exec
	v_mbcnt_lo_u32_b32 v0, s4, 0
	v_mbcnt_hi_u32_b32 v0, s5, v0
	v_cmp_eq_u32_e32 vcc, 0, v0
	s_waitcnt vmcnt(0)
	buffer_inv sc1
	s_and_saveexec_b64 s[6:7], vcc
	s_cbranch_execz .LBB0_1153
	s_bcnt1_i32_b64 s4, s[4:5]
	v_mov_b32_e32 v0, 0x2000
	v_mov_b32_e32 v1, s4
.LBB0_1153:
	s_or_b64 exec, exec, s[6:7]
	s_waitcnt vmcnt(0)

.LBB0_1241:
	s_or_b64 exec, exec, s[4:5]
	s_mov_b64 s[4:5], exec
	v_mbcnt_lo_u32_b32 v0, s4, 0
	v_mbcnt_hi_u32_b32 v0, s5, v0
	v_cmp_eq_u32_e32 vcc, 0, v0
	s_waitcnt vmcnt(0)
	buffer_inv sc1
	s_and_saveexec_b64 s[6:7], vcc
	s_cbranch_execz .LBB0_1243
	s_bcnt1_i32_b64 s4, s[4:5]
	v_mov_b32_e32 v0, 0x2000
	v_mov_b32_e32 v1, s4
.LBB0_1243:
	s_or_b64 exec, exec, s[6:7]
	s_waitcnt vmcnt(0)

.LBB0_1455:
	s_or_b64 exec, exec, s[4:5]
	s_mov_b64 s[4:5], exec
	v_mbcnt_lo_u32_b32 v0, s4, 0
	v_mbcnt_hi_u32_b32 v0, s5, v0
	v_cmp_eq_u32_e32 vcc, 0, v0
	s_waitcnt vmcnt(0)
	buffer_inv sc1
	s_and_saveexec_b64 s[6:7], vcc
	s_cbranch_execz .LBB0_1457
	s_bcnt1_i32_b64 s4, s[4:5]
	v_mov_b32_e32 v0, 0x2000
	v_mov_b32_e32 v1, s4
.LBB0_1457:
	s_or_b64 exec, exec, s[6:7]
	s_waitcnt vmcnt(0)

.LBB0_1551:
	s_or_b64 exec, exec, s[4:5]
	s_mov_b64 s[4:5], exec
	v_mbcnt_lo_u32_b32 v0, s4, 0
	v_mbcnt_hi_u32_b32 v0, s5, v0
	v_cmp_eq_u32_e32 vcc, 0, v0
	s_waitcnt vmcnt(0)
	buffer_inv sc1
	s_and_saveexec_b64 s[6:7], vcc
	s_cbranch_execz .LBB0_1553
	s_bcnt1_i32_b64 s4, s[4:5]
	v_mov_b32_e32 v0, 0x2000
	v_mov_b32_e32 v1, s4
.LBB0_1553:
	s_or_b64 exec, exec, s[6:7]
	s_waitcnt vmcnt(0)

.LBB0_1619:
	s_or_b64 exec, exec, s[4:5]
	s_mov_b64 s[4:5], exec
	v_mbcnt_lo_u32_b32 v0, s4, 0
	v_mbcnt_hi_u32_b32 v0, s5, v0
	v_cmp_eq_u32_e32 vcc, 0, v0
	s_waitcnt vmcnt(0)
	buffer_inv sc1
	s_and_saveexec_b64 s[6:7], vcc
	s_cbranch_execz .LBB0_1621
	s_bcnt1_i32_b64 s4, s[4:5]
	v_mov_b32_e32 v0, 0x2000
	v_mov_b32_e32 v1, s4
.LBB0_1621:
	s_or_b64 exec, exec, s[6:7]
	s_waitcnt vmcnt(0)

.LBB0_1715:
	s_or_b64 exec, exec, s[4:5]
	s_mov_b64 s[4:5], exec
	v_mbcnt_lo_u32_b32 v0, s4, 0
	v_mbcnt_hi_u32_b32 v0, s5, v0
	v_cmp_eq_u32_e32 vcc, 0, v0
	s_waitcnt vmcnt(0)
	buffer_inv sc1
	s_and_saveexec_b64 s[6:7], vcc
	s_cbranch_execz .LBB0_1717
	s_bcnt1_i32_b64 s4, s[4:5]
	v_mov_b32_e32 v0, 0x2000
	v_mov_b32_e32 v1, s4
.LBB0_1717:
	s_or_b64 exec, exec, s[6:7]
	s_waitcnt vmcnt(0)

.LBB0_2005:
	s_or_b64 exec, exec, s[4:5]
	s_mov_b64 s[4:5], exec
	v_mbcnt_lo_u32_b32 v0, s4, 0
	v_mbcnt_hi_u32_b32 v0, s5, v0
	v_cmp_eq_u32_e32 vcc, 0, v0
	s_waitcnt vmcnt(0)
	buffer_inv sc1
	s_and_saveexec_b64 s[6:7], vcc
	s_cbranch_execz .LBB0_2007
	s_bcnt1_i32_b64 s4, s[4:5]
	v_mov_b32_e32 v0, 0x2000
	v_mov_b32_e32 v1, s4
.LBB0_2007:
	s_or_b64 exec, exec, s[6:7]
	s_waitcnt vmcnt(0)

.LBB0_2125:
	s_or_b64 exec, exec, s[4:5]
	s_mov_b64 s[4:5], exec
	v_mbcnt_lo_u32_b32 v0, s4, 0
	v_mbcnt_hi_u32_b32 v0, s5, v0
	v_cmp_eq_u32_e32 vcc, 0, v0
	s_waitcnt vmcnt(0)
	buffer_inv sc1
	s_and_saveexec_b64 s[6:7], vcc
	s_cbranch_execz .LBB0_2127
	s_bcnt1_i32_b64 s4, s[4:5]
	v_mov_b32_e32 v0, 0x2000
	v_mov_b32_e32 v1, s4
.LBB0_2127:
	s_or_b64 exec, exec, s[6:7]
	s_waitcnt vmcnt(0)

.LBB0_2207:
	s_or_b64 exec, exec, s[6:7]
	v_cvt_f32_u32_e32 v4, v2
	s_waitcnt vmcnt(0)
	v_readfirstlane_b32 s4, v3
	v_sub_u32_e32 v3, 0, v2
	v_rcp_iflag_f32_e32 v4, v4
	v_add_u32_e32 v5, s4, v1
	v_mul_f32_e32 v4, 0x4f7ffffe, v4
	v_cvt_u32_f32_e32 v4, v4
	v_mul_lo_u32 v1, v3, v4
	v_mul_hi_u32 v1, v4, v1
	v_add_u32_e32 v1, v4, v1
	v_mul_hi_u32 v1, v5, v1
	v_mul_lo_u32 v3, v1, v2
	v_sub_u32_e32 v3, v5, v3
	v_add_u32_e32 v4, 1, v1
	v_cmp_ge_u32_e32 vcc, v3, v2
	s_nop 1
	v_cndmask_b32_e32 v1, v1, v4, vcc
	v_sub_u32_e32 v4, v3, v2
	v_cndmask_b32_e32 v3, v3, v4, vcc
	v_add_u32_e32 v4, 1, v1
	v_cmp_ge_u32_e32 vcc, v3, v2
	v_add_u32_e32 v3, 1, v5
	s_nop 0
	v_cndmask_b32_e32 v1, v1, v4, vcc
	v_mul_lo_u32 v4, v2, v1
	v_add_u32_e32 v2, v4, v2
	v_cmp_ne_u32_e32 vcc, v3, v2
	s_and_saveexec_b64 s[4:5], vcc
	s_xor_b64 s[4:5], exec, s[4:5]
	s_cbranch_execz .LBB0_2221
	s_waitcnt lgkmcnt(0)
	v_mov_b32_e32 v0, 0
	s_add_u32 s10, s84, 0x4c3500
	s_addc_u32 s11, s85, 0
	global_load_dword v0, v0, s[10:11] sc1
	s_waitcnt vmcnt(0)
	v_cmp_eq_u32_e32 vcc, v0, v1
	s_and_saveexec_b64 s[6:7], vcc
	s_cbranch_execz .LBB0_2220
	s_add_u32 s8, s84, 0x4c0200
	s_addc_u32 s9, s85, 0
	s_mov_b32 s22, 1
	s_mov_b64 s[12:13], 0
	v_mov_b32_e32 v0, 0
	s_branch .LBB0_2211

.LBB0_2238:
	s_or_b64 exec, exec, s[4:5]
	s_mov_b64 s[4:5], exec
	v_mbcnt_lo_u32_b32 v0, s4, 0
	v_mbcnt_hi_u32_b32 v0, s5, v0
	v_cmp_eq_u32_e32 vcc, 0, v0
	s_waitcnt vmcnt(0)
	buffer_inv sc1
	s_and_saveexec_b64 s[6:7], vcc
	s_cbranch_execz .LBB0_2240
	s_bcnt1_i32_b64 s4, s[4:5]
	v_mov_b32_e32 v0, 0x2000
	v_mov_b32_e32 v1, s4
.LBB0_2240:
	s_or_b64 exec, exec, s[6:7]
	s_waitcnt vmcnt(0)

.LBB0_2338:
	s_or_b64 exec, exec, s[4:5]
	s_mov_b64 s[4:5], exec
	v_mbcnt_lo_u32_b32 v0, s4, 0
	v_mbcnt_hi_u32_b32 v0, s5, v0
	v_cmp_eq_u32_e32 vcc, 0, v0
	s_waitcnt vmcnt(0)
	buffer_inv sc1
	s_and_saveexec_b64 s[6:7], vcc
	s_cbranch_execz .LBB0_2340
	s_bcnt1_i32_b64 s4, s[4:5]
	v_mov_b32_e32 v0, 0x2000
	v_mov_b32_e32 v1, s4
.LBB0_2340:
	s_or_b64 exec, exec, s[6:7]
	s_waitcnt vmcnt(0)

.LBB0_2428:
	s_or_b64 exec, exec, s[4:5]
	s_mov_b64 s[4:5], exec
	v_mbcnt_lo_u32_b32 v0, s4, 0
	v_mbcnt_hi_u32_b32 v0, s5, v0
	v_cmp_eq_u32_e32 vcc, 0, v0
	s_waitcnt vmcnt(0)
	buffer_inv sc1
	s_and_saveexec_b64 s[6:7], vcc
	s_cbranch_execz .LBB0_2430
	s_bcnt1_i32_b64 s4, s[4:5]
	v_mov_b32_e32 v0, 0x2000
	v_mov_b32_e32 v1, s4
.LBB0_2430:
	s_or_b64 exec, exec, s[6:7]
	s_waitcnt vmcnt(0)

.LBB0_2496:
	s_or_b64 exec, exec, s[4:5]
	s_mov_b64 s[4:5], exec
	v_mbcnt_lo_u32_b32 v0, s4, 0
	v_mbcnt_hi_u32_b32 v0, s5, v0
	v_cmp_eq_u32_e32 vcc, 0, v0
	s_waitcnt vmcnt(0)
	buffer_inv sc1
	s_and_saveexec_b64 s[6:7], vcc
	s_cbranch_execz .LBB0_2498
	s_bcnt1_i32_b64 s4, s[4:5]
	v_mov_b32_e32 v0, 0x2000
	v_mov_b32_e32 v1, s4
.LBB0_2498:
	s_or_b64 exec, exec, s[6:7]
	s_waitcnt vmcnt(0)
